# every workgroup fires an async L2 writeback behind its barrier-arrival atomic (pre-cleans the L2 for the leader)
# baseline (speedup 1.0000x reference)
.LBB0_53:
	s_mov_b64 s[6:7], exec
	v_readlane_b32 s0, v247, 15
	s_lshl_b32 s0, s0, 8
	v_readlane_b32 s4, v247, 13
	v_mbcnt_lo_u32_b32 v1, s6, 0
	v_readlane_b32 s5, v247, 14
	s_add_u32 s4, s4, s0
	v_mbcnt_hi_u32_b32 v1, s7, v1
	s_addc_u32 s5, s5, 0
	v_cmp_eq_u32_e32 vcc, 0, v1
	s_and_saveexec_b64 s[8:9], vcc
	s_cbranch_execz .LBB0_55
	s_bcnt1_i32_b64 s0, s[6:7]
	v_mov_b32_e32 v3, 0x1000
	v_mov_b32_e32 v4, s0
	global_atomic_add v3, v3, v4, s[4:5] offset:1024 sc0
	buffer_inv sc1
	buffer_wbl2 sc1
.LBB0_55:
	s_or_b64 exec, exec, s[8:9]
	v_cvt_f32_u32_e32 v4, v2
	s_waitcnt vmcnt(1)
	v_readfirstlane_b32 s0, v3
	v_sub_u32_e32 v3, 0, v2
	v_rcp_iflag_f32_e32 v4, v4
	v_add_u32_e32 v5, s0, v1
	v_mul_f32_e32 v4, 0x4f7ffffe, v4
	v_cvt_u32_f32_e32 v4, v4
	v_mul_lo_u32 v1, v3, v4
	v_mul_hi_u32 v1, v4, v1
	v_add_u32_e32 v1, v4, v1
	v_mul_hi_u32 v1, v5, v1
	v_mul_lo_u32 v3, v1, v2
	v_sub_u32_e32 v3, v5, v3
	v_add_u32_e32 v4, 1, v1
	v_cmp_ge_u32_e32 vcc, v3, v2
	s_nop 1
	v_cndmask_b32_e32 v1, v1, v4, vcc
	v_sub_u32_e32 v4, v3, v2
	v_cndmask_b32_e32 v3, v3, v4, vcc
	v_add_u32_e32 v4, 1, v1
	v_cmp_ge_u32_e32 vcc, v3, v2
	v_add_u32_e32 v3, 1, v5
	s_nop 0
	v_cndmask_b32_e32 v1, v1, v4, vcc
	v_mul_lo_u32 v4, v2, v1
	v_add_u32_e32 v2, v4, v2
	v_cmp_ne_u32_e32 vcc, v3, v2
	s_and_saveexec_b64 s[0:1], vcc
	s_xor_b64 s[6:7], exec, s[0:1]
	s_cbranch_execz .LBB0_69
	s_waitcnt lgkmcnt(0)
	v_mov_b32_e32 v0, 0x2000
	global_load_dword v0, v0, s[4:5] offset:1024 sc1
	s_add_u32 s16, s4, 0x2400
	s_addc_u32 s17, s5, 0
	s_waitcnt vmcnt(0)
	v_cmp_eq_u32_e32 vcc, v0, v1
	s_and_saveexec_b64 s[8:9], vcc
	s_cbranch_execz .LBB0_68
	s_add_u32 s14, s92, 0x1200
	s_addc_u32 s15, s93, 0
	s_mov_b32 s0, 1
	s_mov_b64 s[18:19], 0
	v_mov_b32_e32 v0, 0
	s_branch .LBB0_59

.LBB0_311:
	s_or_b64 exec, exec, s[8:9]
	v_cvt_f32_u32_e32 v4, v2
	s_waitcnt vmcnt(1)
	v_readfirstlane_b32 s0, v3
	v_sub_u32_e32 v3, 0, v2
	v_rcp_iflag_f32_e32 v4, v4
	v_add_u32_e32 v5, s0, v1
	v_mul_f32_e32 v4, 0x4f7ffffe, v4
	v_cvt_u32_f32_e32 v4, v4
	v_mul_lo_u32 v1, v3, v4
	v_mul_hi_u32 v1, v4, v1
	v_add_u32_e32 v1, v4, v1
	v_mul_hi_u32 v1, v5, v1
	v_mul_lo_u32 v3, v1, v2
	v_sub_u32_e32 v3, v5, v3
	v_add_u32_e32 v4, 1, v1
	v_cmp_ge_u32_e32 vcc, v3, v2
	s_nop 1
	v_cndmask_b32_e32 v1, v1, v4, vcc
	v_sub_u32_e32 v4, v3, v2
	v_cndmask_b32_e32 v3, v3, v4, vcc
	v_add_u32_e32 v4, 1, v1
	v_cmp_ge_u32_e32 vcc, v3, v2
	v_add_u32_e32 v3, 1, v5
	s_nop 0
	v_cndmask_b32_e32 v1, v1, v4, vcc
	v_mul_lo_u32 v4, v2, v1
	v_add_u32_e32 v2, v4, v2
	v_cmp_ne_u32_e32 vcc, v3, v2
	s_and_saveexec_b64 s[0:1], vcc
	s_xor_b64 s[6:7], exec, s[0:1]
	s_cbranch_execz .LBB0_325
	s_waitcnt lgkmcnt(0)
	v_mov_b32_e32 v0, 0x2000
	global_load_dword v0, v0, s[4:5] offset:1024 sc1
	s_add_u32 s14, s4, 0x2400
	s_addc_u32 s15, s5, 0
	s_waitcnt vmcnt(0)
	v_cmp_eq_u32_e32 vcc, v0, v1
	s_and_saveexec_b64 s[8:9], vcc
	s_cbranch_execz .LBB0_324
	s_add_u32 s12, s92, 0x1200
	s_addc_u32 s13, s93, 0
	s_mov_b32 s0, 1
	s_mov_b64 s[16:17], 0
	v_mov_b32_e32 v0, 0
	s_branch .LBB0_315

.LBB0_675:
	s_mov_b64 s[8:9], exec
	v_readlane_b32 s0, v247, 15
	s_lshl_b32 s0, s0, 8
	v_readlane_b32 s6, v247, 13
	v_mbcnt_lo_u32_b32 v1, s8, 0
	v_readlane_b32 s7, v247, 14
	s_add_u32 s6, s6, s0
	v_mbcnt_hi_u32_b32 v1, s9, v1
	s_addc_u32 s7, s7, 0
	v_cmp_eq_u32_e32 vcc, 0, v1
	s_and_saveexec_b64 s[10:11], vcc
	s_cbranch_execz .LBB0_677
	s_bcnt1_i32_b64 s0, s[8:9]
	v_mov_b32_e32 v3, 0x1000
	v_mov_b32_e32 v4, s0
	global_atomic_add v3, v3, v4, s[6:7] offset:1024 sc0
	buffer_inv sc1
	buffer_wbl2 sc1
.LBB0_677:
	s_or_b64 exec, exec, s[10:11]
	v_cvt_f32_u32_e32 v4, v2
	s_waitcnt vmcnt(1)
	v_readfirstlane_b32 s0, v3
	v_sub_u32_e32 v3, 0, v2
	v_rcp_iflag_f32_e32 v4, v4
	v_add_u32_e32 v5, s0, v1
	v_mul_f32_e32 v4, 0x4f7ffffe, v4
	v_cvt_u32_f32_e32 v4, v4
	v_mul_lo_u32 v1, v3, v4
	v_mul_hi_u32 v1, v4, v1
	v_add_u32_e32 v1, v4, v1
	v_mul_hi_u32 v1, v5, v1
	v_mul_lo_u32 v3, v1, v2
	v_sub_u32_e32 v3, v5, v3
	v_add_u32_e32 v4, 1, v1
	v_cmp_ge_u32_e32 vcc, v3, v2
	s_nop 1
	v_cndmask_b32_e32 v1, v1, v4, vcc
	v_sub_u32_e32 v4, v3, v2
	v_cndmask_b32_e32 v3, v3, v4, vcc
	v_add_u32_e32 v4, 1, v1
	v_cmp_ge_u32_e32 vcc, v3, v2
	v_add_u32_e32 v3, 1, v5
	s_nop 0
	v_cndmask_b32_e32 v1, v1, v4, vcc
	v_mul_lo_u32 v4, v2, v1
	v_add_u32_e32 v2, v4, v2
	v_cmp_ne_u32_e32 vcc, v3, v2
	s_and_saveexec_b64 s[0:1], vcc
	s_xor_b64 s[8:9], exec, s[0:1]
	s_cbranch_execz .LBB0_691
	s_waitcnt lgkmcnt(0)
	v_mov_b32_e32 v0, 0x2000
	global_load_dword v0, v0, s[6:7] offset:1024 sc1
	s_add_u32 s12, s6, 0x2400
	s_addc_u32 s13, s7, 0
	s_waitcnt vmcnt(0)
	v_cmp_eq_u32_e32 vcc, v0, v1
	s_and_saveexec_b64 s[10:11], vcc
	s_cbranch_execz .LBB0_690
	s_mov_b32 s0, 1
	s_mov_b64 s[14:15], 0
	v_mov_b32_e32 v0, 0
	s_branch .LBB0_681
